# attention next-unit warm-up extended from two to four K/V tiles (tiles 2 and 3 are first needed one to two halves after the unit starts)
# baseline (speedup 1.0000x reference)
; #define LAS __attribute__((address_space(3)))
; __global__ void __launch_bounds__(512, 2) trunk_fwd(Args args) {
;     ...
;                     attn::attn_unit(bh >> 3, bh & 7, 15 - i, (const attn::bf16*)(ws + WS_Q), (const attn::bf16*)(ws + WS_KN), (const attn::bf16*)(ws + WS_KPE), (const attn::bf16*)(ws + WS_V), (attn::bf16*)(ws + WS_MIX), (float*)(ws + WS_ASS), (LAS char*)lds);
;                     attn::attn_unit(bh >> 3, bh & 7, i, (const attn::bf16*)(ws + WS_Q), (const attn::bf16*)(ws + WS_KN), (const attn::bf16*)(ws + WS_KPE), (const attn::bf16*)(ws + WS_V), (attn::bf16*)(ws + WS_MIX), (float*)(ws + WS_ASS), (LAS char*)lds);
.Lat_u1_tail:
	s_add_u32 s4, s86, 2
	s_lshl_b32 s5, s4, 16
	s_sub_u32 s5, 0, s5
	s_mov_b32 s53, -1
	s_mov_b32 vcc_lo, s5
	s_mov_b32 vcc_hi, s53
	v_lshl_add_u64 v[168:169], v[126:127], 0, vcc
	global_load_dword v155, v[168:169], off
	v_lshl_add_u64 v[168:169], v[168:169], 0, s[34:35]
	global_load_dword v155, v[168:169], off
	v_lshl_add_u64 v[168:169], v[168:169], 0, s[34:35]
	global_load_dword v155, v[168:169], off
	v_lshl_add_u64 v[168:169], v[168:169], 0, s[34:35]
	global_load_dword v155, v[168:169], off
	v_lshl_add_u64 v[168:169], v[124:125], 0, vcc
	global_load_dword v155, v[168:169], off
	v_lshl_add_u64 v[168:169], v[168:169], 0, s[34:35]
	global_load_dword v155, v[168:169], off
	v_lshl_add_u64 v[168:169], v[168:169], 0, s[34:35]
	global_load_dword v155, v[168:169], off
	v_lshl_add_u64 v[168:169], v[168:169], 0, s[34:35]
	global_load_dword v155, v[168:169], off
	s_lshl_b32 s5, s4, 12
	s_sub_u32 s5, 0, s5
	s_mov_b32 vcc_lo, s5
	v_lshl_add_u64 v[168:169], v[14:15], 0, vcc
	global_load_dword v155, v[168:169], off
	v_lshl_add_u64 v[168:169], v[168:169], 0, s[20:21]
	global_load_dword v155, v[168:169], off
	v_lshl_add_u64 v[168:169], v[168:169], 0, s[20:21]
	global_load_dword v155, v[168:169], off
	v_lshl_add_u64 v[168:169], v[168:169], 0, s[20:21]
	global_load_dword v155, v[168:169], off
	s_lshl_b32 s4, s69, 5
	s_add_u32 s4, s4, s88
	s_mul_i32 s4, s4, 0x600
	s_add_u32 s4, s4, s64
	s_add_u32 s4, s4, s78
	s_addc_u32 s5, s79, 0
	v_mul_u32_u24_e32 v172, 0x600, v140
	global_load_dword v155, v172, s[4:5]
	global_load_dword v155, v172, s[4:5] offset:64
	global_load_dword v155, v172, s[4:5] offset:128
	s_waitcnt lgkmcnt(0)
	s_lshr_b32 s4, s69, 1
	s_sub_u32 s4, s52, s4
	s_sub_u32 s4, s4, 1
	s_cmp_gt_i32 s4, s87
	s_cbranch_scc1 .Lat_u1t_skip
	s_lshl_b32 s4, s50, 13
	s_add_i32 s4, s4, 0x6000
	s_and_b32 s4, s4, 0x6000
	v_add_u32_e32 v159, s4, v144
	ds_read_b64_tr_b16 v[196:197], v159 offset:36864
	ds_read_b64_tr_b16 v[198:199], v159 offset:37376
	ds_read_b64_tr_b16 v[200:201], v159 offset:37888
	ds_read_b64_tr_b16 v[202:203], v159 offset:38400
	ds_read_b64_tr_b16 v[204:205], v159 offset:38912
	ds_read_b64_tr_b16 v[206:207], v159 offset:39424
	ds_read_b64_tr_b16 v[208:209], v159 offset:39936
	ds_read_b64_tr_b16 v[210:211], v159 offset:40448
	ds_read_b64_tr_b16 v[212:213], v159 offset:40960
	ds_read_b64_tr_b16 v[214:215], v159 offset:41472
	ds_read_b64_tr_b16 v[230:231], v159 offset:41984
	ds_read_b64_tr_b16 v[232:233], v159 offset:42496
	ds_read_b64_tr_b16 v[234:235], v159 offset:43008
	ds_read_b64_tr_b16 v[236:237], v159 offset:43520
	ds_read_b64_tr_b16 v[164:165], v159 offset:44032
	ds_read_b64_tr_b16 v[166:167], v159 offset:44544
	v_exp_f32_e32 v238, v238
	v_exp_f32_e32 v239, v239
	v_exp_f32_e32 v240, v240
	v_exp_f32_e32 v241, v241
	v_add_f32_e32 v156, v238, v239
	v_cvt_pk_bf16_f32 v238, v238, v239
	v_add_f32_e32 v157, v240, v241
	v_cvt_pk_bf16_f32 v239, v240, v241
	v_exp_f32_e32 v242, v242
	v_exp_f32_e32 v243, v243
	v_add_f32_e32 v156, v156, v242
	v_add_f32_e32 v156, v156, v243
	v_cvt_pk_bf16_f32 v240, v242, v243
	v_exp_f32_e32 v244, v244
	v_exp_f32_e32 v245, v245
	v_add_f32_e32 v157, v157, v244
	v_add_f32_e32 v157, v157, v245
	v_cvt_pk_bf16_f32 v241, v244, v245
	v_exp_f32_e32 v246, v246
	v_exp_f32_e32 v247, v247
	v_add_f32_e32 v156, v156, v246
	v_add_f32_e32 v156, v156, v247
	v_cvt_pk_bf16_f32 v242, v246, v247
	v_exp_f32_e32 v248, v248
	v_exp_f32_e32 v249, v249
	v_add_f32_e32 v157, v157, v248
	v_add_f32_e32 v157, v157, v249
	v_cvt_pk_bf16_f32 v243, v248, v249
	v_exp_f32_e32 v250, v250
	v_exp_f32_e32 v251, v251
	v_add_f32_e32 v156, v156, v250
	v_add_f32_e32 v156, v156, v251
	v_cvt_pk_bf16_f32 v244, v250, v251
	v_exp_f32_e32 v252, v252
	v_exp_f32_e32 v253, v253
	v_add_f32_e32 v157, v157, v252
	v_add_f32_e32 v157, v157, v253
	v_cvt_pk_bf16_f32 v245, v252, v253
	v_exp_f32_e32 v180, v180
	v_exp_f32_e32 v181, v181
	v_add_f32_e32 v156, v156, v180
	v_add_f32_e32 v156, v156, v181
	v_cvt_pk_bf16_f32 v180, v180, v181
	v_exp_f32_e32 v182, v182
	v_exp_f32_e32 v183, v183
	v_add_f32_e32 v157, v157, v182
	v_add_f32_e32 v157, v157, v183
	v_cvt_pk_bf16_f32 v181, v182, v183
	v_exp_f32_e32 v184, v184
	v_exp_f32_e32 v185, v185
	v_add_f32_e32 v156, v156, v184
	v_add_f32_e32 v156, v156, v185
	v_cvt_pk_bf16_f32 v182, v184, v185
	v_exp_f32_e32 v186, v186
	v_exp_f32_e32 v187, v187
	v_add_f32_e32 v157, v157, v186
	v_add_f32_e32 v157, v157, v187
	v_cvt_pk_bf16_f32 v183, v186, v187
	v_exp_f32_e32 v188, v188
	v_exp_f32_e32 v189, v189
	v_add_f32_e32 v156, v156, v188
	v_add_f32_e32 v156, v156, v189
	v_cvt_pk_bf16_f32 v184, v188, v189
	v_exp_f32_e32 v190, v190
	v_exp_f32_e32 v191, v191
	v_add_f32_e32 v157, v157, v190
	v_add_f32_e32 v157, v157, v191
	v_cvt_pk_bf16_f32 v185, v190, v191
	v_exp_f32_e32 v192, v192
	v_exp_f32_e32 v193, v193
	v_add_f32_e32 v156, v156, v192
	v_add_f32_e32 v156, v156, v193
	v_cvt_pk_bf16_f32 v186, v192, v193
	v_exp_f32_e32 v194, v194
	v_exp_f32_e32 v195, v195
	v_add_f32_e32 v157, v157, v194
	v_add_f32_e32 v157, v157, v195
	v_cvt_pk_bf16_f32 v187, v194, v195
	v_add_f32_e32 v156, v156, v157
	v_add_f32_e32 v128, v128, v156
	s_waitcnt lgkmcnt(0)
	v_mfma_f32_32x32x16_bf16 v[16:31], v[196:199], v[238:241], v[16:31]
	v_mfma_f32_32x32x16_bf16 v[32:47], v[212:215], v[238:241], v[32:47]
	v_mfma_f32_32x32x16_bf16 v[16:31], v[200:203], v[242:245], v[16:31]
	v_mfma_f32_32x32x16_bf16 v[32:47], v[230:233], v[242:245], v[32:47]
	v_mfma_f32_32x32x16_bf16 v[16:31], v[204:207], v[180:183], v[16:31]
	v_mfma_f32_32x32x16_bf16 v[32:47], v[234:237], v[180:183], v[32:47]
	v_mfma_f32_32x32x16_bf16 v[16:31], v[208:211], v[184:187], v[16:31]
	v_mfma_f32_32x32x16_bf16 v[32:47], v[164:167], v[184:187], v[32:47]

; #define LAS __attribute__((address_space(3)))
; __global__ void __launch_bounds__(512, 2) trunk_fwd(Args args) {
;     ...
;                 for (int r = 0; r < 2; ++r) {
;                     const int bh = x * 8 + r * 4 + (c >> 3);
;                     attn::attn_unit(bh >> 3, bh & 7, 15 - i, (const attn::bf16*)(ws + WS_Q), (const attn::bf16*)(ws + WS_KN), (const attn::bf16*)(ws + WS_KPE), (const attn::bf16*)(ws + WS_V), (attn::bf16*)(ws + WS_MIX), (float*)(ws + WS_ASS), (LAS char*)lds);
;                     attn::attn_unit(bh >> 3, bh & 7, i, (const attn::bf16*)(ws + WS_Q), (const attn::bf16*)(ws + WS_KN), (const attn::bf16*)(ws + WS_KPE), (const attn::bf16*)(ws + WS_V), (attn::bf16*)(ws + WS_MIX), (float*)(ws + WS_ASS), (LAS char*)lds);
.Lat_u2_tail:
	s_cmp_eq_u64 s[70:71], 0
	s_cbranch_scc1 .Lat_u2_nowarm
	s_add_u32 s4, s90, 2
	s_lshl_b32 s5, s4, 16
	s_sub_u32 s5, 0, s5
	s_mov_b32 s63, -1
	s_mov_b32 vcc_lo, s5
	s_mov_b32 vcc_hi, s63
	v_lshl_add_u64 v[168:169], v[126:127], 0, vcc
	global_load_dword v155, v[168:169], off offset:512
	v_lshl_add_u64 v[168:169], v[168:169], 0, s[34:35]
	global_load_dword v155, v[168:169], off offset:512
	v_lshl_add_u64 v[168:169], v[168:169], 0, s[34:35]
	global_load_dword v155, v[168:169], off offset:512
	v_lshl_add_u64 v[168:169], v[168:169], 0, s[34:35]
	global_load_dword v155, v[168:169], off offset:512
	v_lshl_add_u64 v[168:169], v[124:125], 0, vcc
	global_load_dword v155, v[168:169], off offset:512
	v_lshl_add_u64 v[168:169], v[168:169], 0, s[34:35]
	global_load_dword v155, v[168:169], off offset:512
	v_lshl_add_u64 v[168:169], v[168:169], 0, s[34:35]
	global_load_dword v155, v[168:169], off offset:512
	v_lshl_add_u64 v[168:169], v[168:169], 0, s[34:35]
	global_load_dword v155, v[168:169], off offset:512
	s_lshl_b32 s5, s4, 12
	s_sub_u32 s5, 0, s5
	s_mov_b32 vcc_lo, s5
	v_lshl_add_u64 v[168:169], v[122:123], 0, vcc
	global_load_dword v155, v[168:169], off
	v_lshl_add_u64 v[168:169], v[168:169], 0, s[20:21]
	global_load_dword v155, v[168:169], off
	v_lshl_add_u64 v[168:169], v[168:169], 0, s[20:21]
	global_load_dword v155, v[168:169], off
	v_lshl_add_u64 v[168:169], v[168:169], 0, s[20:21]
	global_load_dword v155, v[168:169], off
	s_lshl_b32 s4, s56, 5
	s_add_u32 s4, s4, s84
	s_mul_i32 s4, s4, 0x600
	s_add_u32 s4, s4, s64
	s_add_u32 s4, s4, 0x300
	s_add_u32 s4, s4, s78
	s_addc_u32 s5, s79, 0
	v_mul_u32_u24_e32 v172, 0x600, v141
	global_load_dword v155, v172, s[4:5]
	global_load_dword v155, v172, s[4:5] offset:64
	global_load_dword v155, v172, s[4:5] offset:128
